# P3: hand-written ssd_s2 (decay scalars preloaded, state loads 6 chunks ahead, counted waits, stores never waited)
# speedup vs baseline: 1.0090x; 1.0090x over previous
.LBB0_448:
	s_or_b64 exec, exec, s[2:3]
	s_and_b32 s2, s59, 1
	s_cmp_eq_u32 s2, 0
	s_cselect_b64 s[6:7], -1, 0
	s_cmp_eq_u32 s2, 1
	s_cselect_b64 s[2:3], -1, 0
	s_and_b64 vcc, exec, s[2:3]
	s_waitcnt lgkmcnt(0)
	s_barrier
	s_cbranch_vccz .LBB0_453
	s_mov_b32 s2, 0x40000
	v_cmp_gt_i32_e32 vcc, s2, v184
	s_and_saveexec_b64 s[2:3], vcc
	s_cbranch_execz .LBB0_452
	s_add_u32 s4, s76, 0x3cc8000
	s_addc_u32 s5, s77, 0
	s_lshl_b32 s12, s58, 9
	s_add_u32 s8, s74, 0x4200000
	s_addc_u32 s9, s75, 0
	s_mov_b64 s[10:11], 0
	s_mov_b32 s28, 0x3ffff
	v_mov_b32_e32 v10, v184
.Ls2a_loop:
	v_and_b32_e32 v2, 0x7ff, v10
	v_lshlrev_b32_e32 v2, 4, v2
	v_lshrrev_b32_e32 v4, 11, v10
	v_lshl_or_b32 v4, v4, 15, v2
	v_lshrrev_b32_e32 v3, 15, v10
	v_bfe_u32 v243, v10, 11, 4
	v_lshl_or_b32 v2, v243, 15, v2
	v_lshl_or_b32 v2, v3, 23, v2
	v_lshl_or_b32 v3, v3, 8, v243
	v_lshlrev_b32_e32 v3, 2, v3
	global_load_dword v5, v3, s[4:5] offset:0
	global_load_dword v6, v3, s[4:5] offset:64
	global_load_dword v7, v3, s[4:5] offset:128
	global_load_dword v8, v3, s[4:5] offset:192
	global_load_dword v9, v3, s[4:5] offset:256
	global_load_dword v11, v3, s[4:5] offset:320
	global_load_dword v16, v3, s[4:5] offset:384
	global_load_dword v17, v3, s[4:5] offset:448
	global_load_dword v18, v3, s[4:5] offset:512
	global_load_dword v19, v3, s[4:5] offset:576
	global_load_dword v36, v3, s[4:5] offset:640
	global_load_dword v37, v3, s[4:5] offset:704
	global_load_dword v252, v3, s[4:5] offset:768
	global_load_dword v253, v3, s[4:5] offset:832
	global_load_dword v254, v3, s[4:5] offset:896
	global_load_dword v255, v3, s[4:5] offset:960
	s_mov_b64 s[20:21], s[74:75]
	s_mov_b64 s[22:23], s[74:75]
	global_load_dwordx4 v[20:23], v2, s[20:21]
	s_add_u32 s20, s20, 0x80000
	s_addc_u32 s21, s21, 0
	global_load_dwordx4 v[24:27], v2, s[20:21]
	s_add_u32 s20, s20, 0x80000
	s_addc_u32 s21, s21, 0
	global_load_dwordx4 v[28:31], v2, s[20:21]
	s_add_u32 s20, s20, 0x80000
	s_addc_u32 s21, s21, 0
	global_load_dwordx4 v[32:35], v2, s[20:21]
	s_add_u32 s20, s20, 0x80000
	s_addc_u32 s21, s21, 0
	global_load_dwordx4 v[244:247], v2, s[20:21]
	s_add_u32 s20, s20, 0x80000
	s_addc_u32 s21, s21, 0
	global_load_dwordx4 v[248:251], v2, s[20:21]
	s_add_u32 s20, s20, 0x80000
	s_addc_u32 s21, s21, 0
	v_mov_b32_e32 v12, 0
	v_mov_b32_e32 v13, 0
	v_mov_b32_e32 v14, 0
	v_mov_b32_e32 v15, 0
	v_add_u32_e32 v10, s12, v10
	s_waitcnt vmcnt(5)
	global_store_dwordx4 v2, v[12:15], s[22:23]
	s_add_u32 s22, s22, 0x80000
	s_addc_u32 s23, s23, 0
	s_nop 1
	v_fma_f32 v12, v12, v5, v20
	v_fma_f32 v13, v13, v5, v21
	v_fma_f32 v14, v14, v5, v22
	v_fma_f32 v15, v15, v5, v23
	global_load_dwordx4 v[20:23], v2, s[20:21]
	s_add_u32 s20, s20, 0x80000
	s_addc_u32 s21, s21, 0
	s_waitcnt vmcnt(6)
	global_store_dwordx4 v2, v[12:15], s[22:23]
	s_add_u32 s22, s22, 0x80000
	s_addc_u32 s23, s23, 0
	s_nop 1
	v_fma_f32 v12, v12, v6, v24
	v_fma_f32 v13, v13, v6, v25
	v_fma_f32 v14, v14, v6, v26
	v_fma_f32 v15, v15, v6, v27
	global_load_dwordx4 v[24:27], v2, s[20:21]
	s_add_u32 s20, s20, 0x80000
	s_addc_u32 s21, s21, 0
	s_waitcnt vmcnt(7)
	global_store_dwordx4 v2, v[12:15], s[22:23]
	s_add_u32 s22, s22, 0x80000
	s_addc_u32 s23, s23, 0
	s_nop 1
	v_fma_f32 v12, v12, v7, v28
	v_fma_f32 v13, v13, v7, v29
	v_fma_f32 v14, v14, v7, v30
	v_fma_f32 v15, v15, v7, v31
	global_load_dwordx4 v[28:31], v2, s[20:21]
	s_add_u32 s20, s20, 0x80000
	s_addc_u32 s21, s21, 0
	s_waitcnt vmcnt(8)
	global_store_dwordx4 v2, v[12:15], s[22:23]
	s_add_u32 s22, s22, 0x80000
	s_addc_u32 s23, s23, 0
	s_nop 1
	v_fma_f32 v12, v12, v8, v32
	v_fma_f32 v13, v13, v8, v33
	v_fma_f32 v14, v14, v8, v34
	v_fma_f32 v15, v15, v8, v35
	global_load_dwordx4 v[32:35], v2, s[20:21]
	s_add_u32 s20, s20, 0x80000
	s_addc_u32 s21, s21, 0
	s_waitcnt vmcnt(9)
	global_store_dwordx4 v2, v[12:15], s[22:23]
	s_add_u32 s22, s22, 0x80000
	s_addc_u32 s23, s23, 0
	s_nop 1
	v_fma_f32 v12, v12, v9, v244
	v_fma_f32 v13, v13, v9, v245
	v_fma_f32 v14, v14, v9, v246
	v_fma_f32 v15, v15, v9, v247
	global_load_dwordx4 v[244:247], v2, s[20:21]
	s_add_u32 s20, s20, 0x80000
	s_addc_u32 s21, s21, 0
	s_waitcnt vmcnt(10)
	global_store_dwordx4 v2, v[12:15], s[22:23]
	s_add_u32 s22, s22, 0x80000
	s_addc_u32 s23, s23, 0
	s_nop 1
	v_fma_f32 v12, v12, v11, v248
	v_fma_f32 v13, v13, v11, v249
	v_fma_f32 v14, v14, v11, v250
	v_fma_f32 v15, v15, v11, v251
	global_load_dwordx4 v[248:251], v2, s[20:21]
	s_add_u32 s20, s20, 0x80000
	s_addc_u32 s21, s21, 0
	s_waitcnt vmcnt(10)
	global_store_dwordx4 v2, v[12:15], s[22:23]
	s_add_u32 s22, s22, 0x80000
	s_addc_u32 s23, s23, 0
	s_nop 1
	v_fma_f32 v12, v12, v16, v20
	v_fma_f32 v13, v13, v16, v21
	v_fma_f32 v14, v14, v16, v22
	v_fma_f32 v15, v15, v16, v23
	global_load_dwordx4 v[20:23], v2, s[20:21]
	s_add_u32 s20, s20, 0x80000
	s_addc_u32 s21, s21, 0
	s_waitcnt vmcnt(10)
	global_store_dwordx4 v2, v[12:15], s[22:23]
	s_add_u32 s22, s22, 0x80000
	s_addc_u32 s23, s23, 0
	s_nop 1
	v_fma_f32 v12, v12, v17, v24
	v_fma_f32 v13, v13, v17, v25
	v_fma_f32 v14, v14, v17, v26
	v_fma_f32 v15, v15, v17, v27
	global_load_dwordx4 v[24:27], v2, s[20:21]
	s_add_u32 s20, s20, 0x80000
	s_addc_u32 s21, s21, 0
	s_waitcnt vmcnt(10)
	global_store_dwordx4 v2, v[12:15], s[22:23]
	s_add_u32 s22, s22, 0x80000
	s_addc_u32 s23, s23, 0
	s_nop 1
	v_fma_f32 v12, v12, v18, v28
	v_fma_f32 v13, v13, v18, v29
	v_fma_f32 v14, v14, v18, v30
	v_fma_f32 v15, v15, v18, v31
	global_load_dwordx4 v[28:31], v2, s[20:21]
	s_add_u32 s20, s20, 0x80000
	s_addc_u32 s21, s21, 0
	s_waitcnt vmcnt(10)
	global_store_dwordx4 v2, v[12:15], s[22:23]
	s_add_u32 s22, s22, 0x80000
	s_addc_u32 s23, s23, 0
	s_nop 1
	v_fma_f32 v12, v12, v19, v32
	v_fma_f32 v13, v13, v19, v33
	v_fma_f32 v14, v14, v19, v34
	v_fma_f32 v15, v15, v19, v35
	global_load_dwordx4 v[32:35], v2, s[20:21]
	s_add_u32 s20, s20, 0x80000
	s_addc_u32 s21, s21, 0
	s_waitcnt vmcnt(10)
	global_store_dwordx4 v2, v[12:15], s[22:23]
	s_add_u32 s22, s22, 0x80000
	s_addc_u32 s23, s23, 0
	s_nop 1
	v_fma_f32 v12, v12, v36, v244
	v_fma_f32 v13, v13, v36, v245
	v_fma_f32 v14, v14, v36, v246
	v_fma_f32 v15, v15, v36, v247
	s_waitcnt vmcnt(9)
	global_store_dwordx4 v2, v[12:15], s[22:23]
	s_add_u32 s22, s22, 0x80000
	s_addc_u32 s23, s23, 0
	s_nop 1
	v_fma_f32 v12, v12, v37, v248
	v_fma_f32 v13, v13, v37, v249
	v_fma_f32 v14, v14, v37, v250
	v_fma_f32 v15, v15, v37, v251
	s_waitcnt vmcnt(8)
	global_store_dwordx4 v2, v[12:15], s[22:23]
	s_add_u32 s22, s22, 0x80000
	s_addc_u32 s23, s23, 0
	s_nop 1
	v_fma_f32 v12, v12, v252, v20
	v_fma_f32 v13, v13, v252, v21
	v_fma_f32 v14, v14, v252, v22
	v_fma_f32 v15, v15, v252, v23
	s_waitcnt vmcnt(7)
	global_store_dwordx4 v2, v[12:15], s[22:23]
	s_add_u32 s22, s22, 0x80000
	s_addc_u32 s23, s23, 0
	s_nop 1
	v_fma_f32 v12, v12, v253, v24
	v_fma_f32 v13, v13, v253, v25
	v_fma_f32 v14, v14, v253, v26
	v_fma_f32 v15, v15, v253, v27
	s_waitcnt vmcnt(6)
	global_store_dwordx4 v2, v[12:15], s[22:23]
	s_add_u32 s22, s22, 0x80000
	s_addc_u32 s23, s23, 0
	s_nop 1
	v_fma_f32 v12, v12, v254, v28
	v_fma_f32 v13, v13, v254, v29
	v_fma_f32 v14, v14, v254, v30
	v_fma_f32 v15, v15, v254, v31
	s_waitcnt vmcnt(5)
	global_store_dwordx4 v2, v[12:15], s[22:23]
	s_add_u32 s22, s22, 0x80000
	s_addc_u32 s23, s23, 0
	s_nop 1
	v_fma_f32 v12, v12, v255, v32
	v_fma_f32 v13, v13, v255, v33
	v_fma_f32 v14, v14, v255, v34
	v_fma_f32 v15, v15, v255, v35
	s_nop 0
	global_store_dwordx4 v4, v[12:15], s[8:9]
	v_cmp_lt_i32_e32 vcc, s28, v10
	s_or_b64 s[10:11], vcc, s[10:11]
	s_andn2_b64 exec, exec, s[10:11]
	s_cbranch_execnz .Ls2a_loop

.LBB0_470:
	s_and_b64 vcc, exec, s[6:7]
	s_cbranch_vccz .LBB0_475
	s_mov_b32 s2, 0x40000
	v_cmp_gt_i32_e32 vcc, s2, v184
	s_and_saveexec_b64 s[2:3], vcc
	s_cbranch_execz .LBB0_474
	s_add_u32 s4, s76, 0x3cc8000
	s_addc_u32 s5, s77, 0
	s_lshl_b32 s12, s58, 9
	s_add_u32 s8, s74, 0x4200000
	s_addc_u32 s9, s75, 0
	s_mov_b64 s[10:11], 0
	s_mov_b32 s28, 0x3ffff
	v_mov_b32_e32 v10, v184
